# EpiF epilogue (DFT-B GEMM) rewritten: n0/n1 quads paired by permlane16_swap, 16-byte stores
# speedup vs baseline: 1.0070x; 1.0070x over previous
; __device__ __forceinline__ unsigned cvt_pk_bf16(float lo, float hi) { unsigned r; asm("v_cvt_pk_bf16_f32 %0, %1, %2" : "=v"(r) : "v"(lo), "v"(hi)); return r; }
;     __device__ __forceinline__ void operator()(const Acc& acc, const Unit& u, int wr, int wc, int fr, int fq) const {
;         const int row0 = u.pm * 256 + wr * 64 + fr, col0 = u.pn * 256 + wc * 32 + 4 * fq;
; #pragma unroll
;         for (int ai = 0; ai < 2; ++ai)
; #pragma unroll
;             for (int m = 0; m < 4; ++m) { bf16_t* rp = F + (size_t)(row0 + ai * 128 + m * 16) * 1024 + col0;
; #pragma unroll
;                 for (int bj = 0; bj < 2; ++bj)
; #pragma unroll
;                     for (int n = 0; n < 2; ++n) { const f32x4 a = acc[ai][bj][m][n] * (1.0f / 1024.0f); u32x2 w; w.x = cvt_pk_bf16(a[0], a[1]); w.y = cvt_pk_bf16(a[2], a[3]); *(u32x2*)(rp + bj * 128 + n * 16) = w; } }
.LBB0_1664:
	v_bfe_u32 v147, v206, 4, 1
	v_mul_u32_u24_e32 v147, 24, v147
	v_add_u32_e32 v147, v147, v153
	v_lshl_or_b32 v147, s68, 9, v147
	v_lshl_add_u32 v146, s69, 8, v148
	v_lshl_add_u32 v146, v146, 11, v147
	v_pk_mul_f32 v[124:125], v[124:125], s[28:29] op_sel_hi:[1,0]
	v_pk_mul_f32 v[126:127], v[126:127], s[28:29] op_sel_hi:[1,0]
	v_pk_mul_f32 v[120:121], v[120:121], s[28:29] op_sel_hi:[1,0]
	v_pk_mul_f32 v[122:123], v[122:123], s[28:29] op_sel_hi:[1,0]
	v_cvt_pk_bf16_f32 v124, v124, v125
	v_cvt_pk_bf16_f32 v125, v126, v127
	v_cvt_pk_bf16_f32 v126, v120, v121
	v_cvt_pk_bf16_f32 v127, v122, v123
	s_nop 1
	v_permlane16_swap_b32_e32 v124, v126
	v_permlane16_swap_b32_e32 v125, v127
	global_store_dwordx4 v146, v[124:127], s[14:15]
	v_pk_mul_f32 v[116:117], v[116:117], s[28:29] op_sel_hi:[1,0]
	v_pk_mul_f32 v[118:119], v[118:119], s[28:29] op_sel_hi:[1,0]
	v_pk_mul_f32 v[108:109], v[108:109], s[28:29] op_sel_hi:[1,0]
	v_pk_mul_f32 v[110:111], v[110:111], s[28:29] op_sel_hi:[1,0]
	v_cvt_pk_bf16_f32 v116, v116, v117
	v_cvt_pk_bf16_f32 v117, v118, v119
	v_cvt_pk_bf16_f32 v118, v108, v109
	v_cvt_pk_bf16_f32 v119, v110, v111
	s_nop 1
	v_permlane16_swap_b32_e32 v116, v118
	v_permlane16_swap_b32_e32 v117, v119
	global_store_dwordx4 v146, v[116:119], s[14:15] offset:256
	v_add_u32_e32 v145, 0x8000, v146
	v_pk_mul_f32 v[112:113], v[112:113], s[28:29] op_sel_hi:[1,0]
	v_pk_mul_f32 v[114:115], v[114:115], s[28:29] op_sel_hi:[1,0]
	v_pk_mul_f32 v[104:105], v[104:105], s[28:29] op_sel_hi:[1,0]
	v_pk_mul_f32 v[106:107], v[106:107], s[28:29] op_sel_hi:[1,0]
	v_cvt_pk_bf16_f32 v112, v112, v113
	v_cvt_pk_bf16_f32 v113, v114, v115
	v_cvt_pk_bf16_f32 v114, v104, v105
	v_cvt_pk_bf16_f32 v115, v106, v107
	s_nop 1
	v_permlane16_swap_b32_e32 v112, v114
	v_permlane16_swap_b32_e32 v113, v115
	global_store_dwordx4 v145, v[112:115], s[14:15]
	v_pk_mul_f32 v[100:101], v[100:101], s[28:29] op_sel_hi:[1,0]
	v_pk_mul_f32 v[102:103], v[102:103], s[28:29] op_sel_hi:[1,0]
	v_pk_mul_f32 v[92:93], v[92:93], s[28:29] op_sel_hi:[1,0]
	v_pk_mul_f32 v[94:95], v[94:95], s[28:29] op_sel_hi:[1,0]
	v_cvt_pk_bf16_f32 v100, v100, v101
	v_cvt_pk_bf16_f32 v101, v102, v103
	v_cvt_pk_bf16_f32 v102, v92, v93
	v_cvt_pk_bf16_f32 v103, v94, v95
	s_nop 1
	v_permlane16_swap_b32_e32 v100, v102
	v_permlane16_swap_b32_e32 v101, v103
	global_store_dwordx4 v145, v[100:103], s[14:15] offset:256
	v_add_u32_e32 v144, 0x10000, v146
	v_pk_mul_f32 v[96:97], v[96:97], s[28:29] op_sel_hi:[1,0]
	v_pk_mul_f32 v[98:99], v[98:99], s[28:29] op_sel_hi:[1,0]
	v_pk_mul_f32 v[88:89], v[88:89], s[28:29] op_sel_hi:[1,0]
	v_pk_mul_f32 v[90:91], v[90:91], s[28:29] op_sel_hi:[1,0]
	v_cvt_pk_bf16_f32 v96, v96, v97
	v_cvt_pk_bf16_f32 v97, v98, v99
	v_cvt_pk_bf16_f32 v98, v88, v89
	v_cvt_pk_bf16_f32 v99, v90, v91
	s_nop 1
	v_permlane16_swap_b32_e32 v96, v98
	v_permlane16_swap_b32_e32 v97, v99
	global_store_dwordx4 v144, v[96:99], s[14:15]
	v_pk_mul_f32 v[84:85], v[84:85], s[28:29] op_sel_hi:[1,0]
	v_pk_mul_f32 v[86:87], v[86:87], s[28:29] op_sel_hi:[1,0]
	v_pk_mul_f32 v[76:77], v[76:77], s[28:29] op_sel_hi:[1,0]
	v_pk_mul_f32 v[78:79], v[78:79], s[28:29] op_sel_hi:[1,0]
	v_cvt_pk_bf16_f32 v84, v84, v85
	v_cvt_pk_bf16_f32 v85, v86, v87
	v_cvt_pk_bf16_f32 v86, v76, v77
	v_cvt_pk_bf16_f32 v87, v78, v79
	s_nop 1
	v_permlane16_swap_b32_e32 v84, v86
	v_permlane16_swap_b32_e32 v85, v87
	global_store_dwordx4 v144, v[84:87], s[14:15] offset:256
	v_add_u32_e32 v145, 0x18000, v146
	v_pk_mul_f32 v[80:81], v[80:81], s[28:29] op_sel_hi:[1,0]
	v_pk_mul_f32 v[82:83], v[82:83], s[28:29] op_sel_hi:[1,0]
	v_pk_mul_f32 v[72:73], v[72:73], s[28:29] op_sel_hi:[1,0]
	v_pk_mul_f32 v[74:75], v[74:75], s[28:29] op_sel_hi:[1,0]
	v_cvt_pk_bf16_f32 v80, v80, v81
	v_cvt_pk_bf16_f32 v81, v82, v83
	v_cvt_pk_bf16_f32 v82, v72, v73
	v_cvt_pk_bf16_f32 v83, v74, v75
	s_nop 1
	v_permlane16_swap_b32_e32 v80, v82
	v_permlane16_swap_b32_e32 v81, v83
	global_store_dwordx4 v145, v[80:83], s[14:15]
	v_pk_mul_f32 v[68:69], v[68:69], s[28:29] op_sel_hi:[1,0]
	v_pk_mul_f32 v[70:71], v[70:71], s[28:29] op_sel_hi:[1,0]
	v_pk_mul_f32 v[64:65], v[64:65], s[28:29] op_sel_hi:[1,0]
	v_pk_mul_f32 v[66:67], v[66:67], s[28:29] op_sel_hi:[1,0]
	v_cvt_pk_bf16_f32 v68, v68, v69
	v_cvt_pk_bf16_f32 v69, v70, v71
	v_cvt_pk_bf16_f32 v70, v64, v65
	v_cvt_pk_bf16_f32 v71, v66, v67
	s_nop 1
	v_permlane16_swap_b32_e32 v68, v70
; __device__ __forceinline__ unsigned cvt_pk_bf16(float lo, float hi) { unsigned r; asm("v_cvt_pk_bf16_f32 %0, %1, %2" : "=v"(r) : "v"(lo), "v"(hi)); return r; }
;     __device__ __forceinline__ void operator()(const Acc& acc, const Unit& u, int wr, int wc, int fr, int fq) const {
;         const int row0 = u.pm * 256 + wr * 64 + fr, col0 = u.pn * 256 + wc * 32 + 4 * fq;
; #pragma unroll
;         for (int ai = 0; ai < 2; ++ai)
; #pragma unroll
;             for (int m = 0; m < 4; ++m) { bf16_t* rp = F + (size_t)(row0 + ai * 128 + m * 16) * 1024 + col0;
; #pragma unroll
;                 for (int bj = 0; bj < 2; ++bj)
; #pragma unroll
;                     for (int n = 0; n < 2; ++n) { const f32x4 a = acc[ai][bj][m][n] * (1.0f / 1024.0f); u32x2 w; w.x = cvt_pk_bf16(a[0], a[1]); w.y = cvt_pk_bf16(a[2], a[3]); *(u32x2*)(rp + bj * 128 + n * 16) = w; } }
	v_permlane16_swap_b32_e32 v69, v71
	global_store_dwordx4 v145, v[68:71], s[14:15] offset:256
	v_add_u32_e32 v144, 0x40000, v146
	v_pk_mul_f32 v[60:61], v[60:61], s[28:29] op_sel_hi:[1,0]
	v_pk_mul_f32 v[62:63], v[62:63], s[28:29] op_sel_hi:[1,0]
	v_pk_mul_f32 v[56:57], v[56:57], s[28:29] op_sel_hi:[1,0]
	v_pk_mul_f32 v[58:59], v[58:59], s[28:29] op_sel_hi:[1,0]
	v_cvt_pk_bf16_f32 v60, v60, v61
	v_cvt_pk_bf16_f32 v61, v62, v63
	v_cvt_pk_bf16_f32 v62, v56, v57
	v_cvt_pk_bf16_f32 v63, v58, v59
	s_nop 1
	v_permlane16_swap_b32_e32 v60, v62
	v_permlane16_swap_b32_e32 v61, v63
	global_store_dwordx4 v144, v[60:63], s[14:15]
	v_pk_mul_f32 v[52:53], v[52:53], s[28:29] op_sel_hi:[1,0]
	v_pk_mul_f32 v[54:55], v[54:55], s[28:29] op_sel_hi:[1,0]
	v_pk_mul_f32 v[44:45], v[44:45], s[28:29] op_sel_hi:[1,0]
	v_pk_mul_f32 v[46:47], v[46:47], s[28:29] op_sel_hi:[1,0]
	v_cvt_pk_bf16_f32 v52, v52, v53
	v_cvt_pk_bf16_f32 v53, v54, v55
	v_cvt_pk_bf16_f32 v54, v44, v45
	v_cvt_pk_bf16_f32 v55, v46, v47
	s_nop 1
	v_permlane16_swap_b32_e32 v52, v54
	v_permlane16_swap_b32_e32 v53, v55
	global_store_dwordx4 v144, v[52:55], s[14:15] offset:256
	v_add_u32_e32 v145, 0x48000, v146
	v_pk_mul_f32 v[48:49], v[48:49], s[28:29] op_sel_hi:[1,0]
	v_pk_mul_f32 v[50:51], v[50:51], s[28:29] op_sel_hi:[1,0]
	v_pk_mul_f32 v[40:41], v[40:41], s[28:29] op_sel_hi:[1,0]
	v_pk_mul_f32 v[42:43], v[42:43], s[28:29] op_sel_hi:[1,0]
	v_cvt_pk_bf16_f32 v48, v48, v49
	v_cvt_pk_bf16_f32 v49, v50, v51
	v_cvt_pk_bf16_f32 v50, v40, v41
	v_cvt_pk_bf16_f32 v51, v42, v43
	s_nop 1
	v_permlane16_swap_b32_e32 v48, v50
	v_permlane16_swap_b32_e32 v49, v51
	global_store_dwordx4 v145, v[48:51], s[14:15]
	v_pk_mul_f32 v[36:37], v[36:37], s[28:29] op_sel_hi:[1,0]
	v_pk_mul_f32 v[38:39], v[38:39], s[28:29] op_sel_hi:[1,0]
	v_pk_mul_f32 v[28:29], v[28:29], s[28:29] op_sel_hi:[1,0]
	v_pk_mul_f32 v[30:31], v[30:31], s[28:29] op_sel_hi:[1,0]
	v_cvt_pk_bf16_f32 v36, v36, v37
	v_cvt_pk_bf16_f32 v37, v38, v39
	v_cvt_pk_bf16_f32 v38, v28, v29
	v_cvt_pk_bf16_f32 v39, v30, v31
	s_nop 1
	v_permlane16_swap_b32_e32 v36, v38
	v_permlane16_swap_b32_e32 v37, v39
	global_store_dwordx4 v145, v[36:39], s[14:15] offset:256
	v_add_u32_e32 v144, 0x50000, v146
	v_pk_mul_f32 v[32:33], v[32:33], s[28:29] op_sel_hi:[1,0]
	v_pk_mul_f32 v[34:35], v[34:35], s[28:29] op_sel_hi:[1,0]
	v_pk_mul_f32 v[24:25], v[24:25], s[28:29] op_sel_hi:[1,0]
	v_pk_mul_f32 v[26:27], v[26:27], s[28:29] op_sel_hi:[1,0]
	v_cvt_pk_bf16_f32 v32, v32, v33
	v_cvt_pk_bf16_f32 v33, v34, v35
	v_cvt_pk_bf16_f32 v34, v24, v25
	v_cvt_pk_bf16_f32 v35, v26, v27
	s_nop 1
	v_permlane16_swap_b32_e32 v32, v34
	v_permlane16_swap_b32_e32 v33, v35
	global_store_dwordx4 v144, v[32:35], s[14:15]
	v_pk_mul_f32 v[20:21], v[20:21], s[28:29] op_sel_hi:[1,0]
	v_pk_mul_f32 v[22:23], v[22:23], s[28:29] op_sel_hi:[1,0]
	v_pk_mul_f32 v[12:13], v[12:13], s[28:29] op_sel_hi:[1,0]
	v_pk_mul_f32 v[14:15], v[14:15], s[28:29] op_sel_hi:[1,0]
	v_cvt_pk_bf16_f32 v20, v20, v21
	v_cvt_pk_bf16_f32 v21, v22, v23
	v_cvt_pk_bf16_f32 v22, v12, v13
	v_cvt_pk_bf16_f32 v23, v14, v15
	s_nop 1
	v_permlane16_swap_b32_e32 v20, v22
	v_permlane16_swap_b32_e32 v21, v23
	global_store_dwordx4 v144, v[20:23], s[14:15] offset:256
	v_add_u32_e32 v145, 0x58000, v146
	v_pk_mul_f32 v[16:17], v[16:17], s[28:29] op_sel_hi:[1,0]
	v_pk_mul_f32 v[18:19], v[18:19], s[28:29] op_sel_hi:[1,0]
	v_pk_mul_f32 v[8:9], v[8:9], s[28:29] op_sel_hi:[1,0]
	v_pk_mul_f32 v[10:11], v[10:11], s[28:29] op_sel_hi:[1,0]
	v_cvt_pk_bf16_f32 v16, v16, v17
	v_cvt_pk_bf16_f32 v17, v18, v19
	v_cvt_pk_bf16_f32 v18, v8, v9
	v_cvt_pk_bf16_f32 v19, v10, v11
	s_nop 1
	v_permlane16_swap_b32_e32 v16, v18
	v_permlane16_swap_b32_e32 v17, v19
	global_store_dwordx4 v145, v[16:19], s[14:15]
	v_pk_mul_f32 v[4:5], v[4:5], s[28:29] op_sel_hi:[1,0]
	v_pk_mul_f32 v[6:7], v[6:7], s[28:29] op_sel_hi:[1,0]
	v_pk_mul_f32 v[0:1], v[0:1], s[28:29] op_sel_hi:[1,0]
	v_pk_mul_f32 v[2:3], v[2:3], s[28:29] op_sel_hi:[1,0]
	v_cvt_pk_bf16_f32 v4, v4, v5
	v_cvt_pk_bf16_f32 v5, v6, v7
	v_cvt_pk_bf16_f32 v6, v0, v1
	v_cvt_pk_bf16_f32 v7, v2, v3
	s_nop 1
	v_permlane16_swap_b32_e32 v4, v6
	v_permlane16_swap_b32_e32 v5, v7
	global_store_dwordx4 v145, v[4:7], s[14:15] offset:256
	s_andn2_b64 vcc, exec, s[6:7]
	s_mov_b64 s[6:7], -1
	s_cbranch_vccnz .LBB0_1659
	s_andn2_b64 vcc, exec, s[22:23]
	s_cbranch_vccnz .LBB0_1658
	s_barrier
	s_branch .LBB0_1658
